# FFN-in epilogues: per-row rstd cached in spare VGPRs across tiles of the same row block (tag = pm+1), recomputed on a miss
# speedup vs baseline: 1.0222x; 1.0139x over previous
.LBB0_238:
	s_andn2_b64 vcc, exec, s[38:39]
	s_cbranch_vccnz .LBB0_446
	s_waitcnt vmcnt(7)
	v_mov_b32_e32 v0, v155
	v_writelane_b32 v244, 0, 0
	v_readlane_b32 s8, v254, 0
	s_waitcnt vmcnt(5)
	v_mov_b32_e32 v9, v155
	s_cmpk_gt_i32 s8, 0x57f
	v_readfirstlane_b32 s33, v9
	s_cbranch_scc1 .LBB0_255
	v_lshlrev_b32_e32 v0, 4, v9
	v_add_u32_e32 v1, 0x2000, v0
	v_ashrrev_i32_e32 v2, 31, v1
	v_lshrrev_b32_e32 v2, 22, v2
	v_add_u32_e32 v2, v1, v2
	v_ashrrev_i32_e32 v8, 10, v2
	v_mul_i32_i24_e32 v3, 0x400, v8
	v_sub_u32_e32 v1, v1, v3
	v_lshrrev_b32_e32 v3, 4, v1
	v_bitop3_b32 v1, v3, v1, 32 bitop3:0x6c
	v_ashrrev_i32_e32 v3, 31, v1
	v_lshrrev_b32_e32 v3, 26, v3
	v_add_u32_e32 v3, v1, v3
	v_ashrrev_i32_e32 v10, 6, v3
	v_and_b32_e32 v3, 0xc0, v3
	s_ashr_i32 s18, s8, 31
	v_sub_u32_e32 v1, v1, v3
	s_lshr_b32 s18, s18, 29
	v_lshlrev_b32_e32 v2, 5, v8
	v_ashrrev_i16_sdwa v1, v204, sext(v1) dst_sel:DWORD dst_unused:UNUSED_PAD src0_sel:DWORD src1_sel:BYTE_0
	s_add_i32 s18, s8, s18
	s_ashr_i32 s6, s33, 6
	v_and_b32_e32 v2, 32, v2
	v_bfe_i32 v11, v1, 0, 16
	s_ashr_i32 s20, s18, 3
	s_and_b32 s18, s18, -8
	s_ashr_i32 s42, s33, 8
	s_lshl_b32 s9, s6, 10
	v_add_u32_e32 v1, v2, v11
	v_lshlrev_b32_e32 v2, 3, v8
	s_sub_i32 s18, s8, s18
	v_and_b32_e32 v2, 0x1ffff0, v2
	s_cmp_lt_i32 s18, 0
	s_movk_i32 s21, 0xb1
	v_add_lshl_u32 v2, v10, v2, 11
	s_cselect_b32 s21, s21, 0xb0
	s_waitcnt vmcnt(1)
	v_lshl_add_u32 v130, v1, 1, v2
	v_bfe_i32 v2, v9, 27, 1
	s_mul_i32 s18, s18, s21
	v_lshrrev_b32_e32 v2, 22, v2
	s_add_i32 s18, s18, s20
	v_add_u32_e32 v2, v0, v2
	s_mul_hi_i32 s20, s18, 0x2e8ba2e9
	v_and_b32_e32 v2, 0xfffffc00, v2
	s_lshr_b32 s21, s20, 31
	s_ashr_i32 s20, s20, 5
	v_sub_u32_e32 v0, v0, v2
	s_add_i32 s20, s20, s21
	v_lshrrev_b32_e32 v2, 4, v0
	s_lshl_b32 s21, s20, 3
	s_mulk_i32 s20, 0xb0
	v_bitop3_b32 v0, v2, v0, 32 bitop3:0x6c
	s_sub_i32 s18, s18, s20
	v_ashrrev_i32_e32 v2, 31, v0
	s_bfe_u32 s20, s18, 0x3001c
	v_ashrrev_i32_e32 v1, 31, v9
	v_lshrrev_b32_e32 v2, 26, v2
	s_add_i32 s20, s18, s20
	v_lshrrev_b32_e32 v1, 26, v1
	v_add_u32_e32 v2, v0, v2
	s_sext_i32_i16 s24, s20
	s_and_b32 s20, s20, 0xfff8
	v_add_u32_e32 v1, v9, v1
	s_waitcnt vmcnt(4)
	v_ashrrev_i32_e32 v13, 6, v2
	v_and_b32_e32 v2, 0xc0, v2
	s_sub_i32 s18, s18, s20
	v_ashrrev_i32_e32 v12, 6, v1
	v_sub_u32_e32 v0, v0, v2
	s_sext_i32_i16 s18, s18
	v_lshlrev_b32_e32 v1, 5, v12
	v_ashrrev_i16_sdwa v0, v204, sext(v0) dst_sel:DWORD dst_unused:UNUSED_PAD src0_sel:DWORD src1_sel:BYTE_0
	s_lshr_b32 s24, s24, 3
	s_add_i32 s38, s21, s18
	v_and_b32_e32 v1, 32, v1
	v_bfe_i32 v14, v0, 0, 16
	s_ashr_i32 s39, s38, 31
	s_bfe_i64 s[26:27], s[24:25], 0x100000
	v_add_u32_e32 v0, v1, v14
	v_lshlrev_b32_e32 v1, 3, v12
	s_lshl_b64 s[20:21], s[38:39], 19
	s_lshl_b64 s[26:27], s[26:27], 19
	v_readlane_b32 s40, v255, 29
	v_and_b32_e32 v1, 0x1ffff0, v1
	v_readlane_b32 s41, v255, 30
	s_add_u32 s56, s40, s26
	v_add_lshl_u32 v1, v13, v1, 11
	s_addc_u32 s57, s41, s27
	s_add_i32 s60, s9, 0
	v_lshl_add_u32 v132, v0, 1, v1
	s_add_i32 m0, s60, 0x10000
	v_mov_b32_e32 v133, v49
	global_load_lds_dwordx4 v132, s[56:57]
	s_add_i32 m0, s60, 0x12000
	s_add_u32 s26, s56, 0x40000
	global_load_lds_dwordx4 v130, s[56:57]
	s_addc_u32 s27, s57, 0
	s_add_i32 m0, s60, 0x14000
	v_mov_b32_e32 v131, v49
	global_load_lds_dwordx4 v132, s[26:27]
	s_add_i32 m0, s60, 0x16000
	s_add_u32 s54, s16, s20
	s_addc_u32 s55, s17, s21
	s_add_i32 s61, s60, 0x2000
	global_load_lds_dwordx4 v130, s[26:27]
	s_mov_b32 m0, s60
	s_add_u32 s20, s54, 0x40000
	global_load_lds_dwordx4 v132, s[54:55]
	s_mov_b32 m0, s61
	s_addc_u32 s21, s55, 0
	s_add_i32 s62, s60, 0x4000
	global_load_lds_dwordx4 v130, s[54:55]
	s_mov_b32 m0, s62
	s_add_i32 s63, s60, 0x6000
	global_load_lds_dwordx4 v132, s[20:21]
	s_mov_b32 m0, s63
	s_cmp_eq_u32 s42, 1
	global_load_lds_dwordx4 v130, s[20:21]
	v_lshl_add_u64 v[6:7], s[56:57], 0, v[132:133]
	v_lshl_add_u64 v[4:5], s[56:57], 0, v[130:131]
	v_lshl_add_u64 v[0:1], s[54:55], 0, v[132:133]
	s_cselect_b64 s[40:41], -1, 0
	s_cmp_lg_u32 s42, 1
	v_lshl_add_u64 v[2:3], s[54:55], 0, v[130:131]
	s_cbranch_scc1 .LBB0_242
	s_barrier

.LBB0_251:
	v_lshl_add_u32 v177, s38, 8, v172
	s_add_i32 s20, s38, 1
	v_readlane_b32 s6, v244, 0
	s_nop 1
	s_cmp_eq_u32 s6, s20
	s_cbranch_scc1 .Lrs_hit1
	v_add_u32_e32 v48, v177, v174
	v_add_u32_e32 v140, 0x40a0, v48
	v_mov_b32_e32 v141, v49
	v_lshl_add_u64 v[138:139], v[48:49], 2, s[22:23]
	v_lshl_add_u64 v[140:141], v[140:141], 2, s[22:23]
	global_load_dword v168, v[138:139], off
	global_load_dword v152, v[140:141], off
	v_add_u32_e32 v138, 0x4000, v48
	v_mov_b32_e32 v139, v49
	v_add_u32_e32 v156, 0x40b0, v48
	v_mov_b32_e32 v157, v49
	v_lshl_add_u64 v[138:139], v[138:139], 2, s[22:23]
	v_lshl_add_u64 v[156:157], v[156:157], 2, s[22:23]
	global_load_dword v170, v[138:139], off
	v_add_u32_e32 v140, 0x80a0, v48
	global_load_dword v156, v[156:157], off
	v_add_u32_e32 v138, 0x8000, v48
	v_mov_b32_e32 v139, v49
	v_lshl_add_u64 v[138:139], v[138:139], 2, s[22:23]
	global_load_dword v169, v[138:139], off
	v_add_u32_e32 v138, 0xc000, v48
	v_mov_b32_e32 v139, v49
	v_lshl_add_u64 v[138:139], v[138:139], 2, s[22:23]
	global_load_dword v171, v[138:139], off
	v_or_b32_e32 v138, 16, v48
	v_mov_b32_e32 v139, v49
	v_lshl_add_u64 v[138:139], v[138:139], 2, s[22:23]
	global_load_dword v150, v[138:139], off
	v_add_u32_e32 v138, 0x4010, v48
	v_mov_b32_e32 v139, v49
	v_lshl_add_u64 v[138:139], v[138:139], 2, s[22:23]
	global_load_dword v166, v[138:139], off
	v_add_u32_e32 v138, 0x8010, v48
	v_mov_b32_e32 v139, v49
	v_lshl_add_u64 v[138:139], v[138:139], 2, s[22:23]
	global_load_dword v151, v[138:139], off
	v_add_u32_e32 v138, 0xc010, v48
	v_mov_b32_e32 v139, v49
	v_lshl_add_u64 v[138:139], v[138:139], 2, s[22:23]
	global_load_dword v167, v[138:139], off
	v_or_b32_e32 v138, 32, v48
	v_mov_b32_e32 v139, v49
	v_lshl_add_u64 v[138:139], v[138:139], 2, s[22:23]
	global_load_dword v146, v[138:139], off
	v_add_u32_e32 v138, 0x4020, v48
	v_mov_b32_e32 v139, v49
	v_lshl_add_u64 v[138:139], v[138:139], 2, s[22:23]
	global_load_dword v162, v[138:139], off
	v_add_u32_e32 v138, 0x8020, v48
	v_mov_b32_e32 v139, v49
	v_lshl_add_u64 v[138:139], v[138:139], 2, s[22:23]
	global_load_dword v147, v[138:139], off
	v_add_u32_e32 v138, 0xc020, v48
	v_mov_b32_e32 v139, v49
	v_lshl_add_u64 v[138:139], v[138:139], 2, s[22:23]
	global_load_dword v163, v[138:139], off
	v_or_b32_e32 v138, 48, v48
	v_mov_b32_e32 v139, v49
	v_lshl_add_u64 v[138:139], v[138:139], 2, s[22:23]
	global_load_dword v148, v[138:139], off
	v_add_u32_e32 v138, 0x4030, v48
	v_mov_b32_e32 v139, v49
	v_lshl_add_u64 v[138:139], v[138:139], 2, s[22:23]
	global_load_dword v164, v[138:139], off
	v_add_u32_e32 v138, 0x8030, v48
	v_mov_b32_e32 v139, v49
	v_lshl_add_u64 v[138:139], v[138:139], 2, s[22:23]
	global_load_dword v149, v[138:139], off
	v_add_u32_e32 v138, 0xc030, v48
	v_mov_b32_e32 v139, v49
	v_lshl_add_u64 v[138:139], v[138:139], 2, s[22:23]
	global_load_dword v165, v[138:139], off
	v_add_u32_e32 v138, 0x80, v48
	v_mov_b32_e32 v139, v49
	v_lshl_add_u64 v[138:139], v[138:139], 2, s[22:23]
	global_load_dword v142, v[138:139], off
	v_add_u32_e32 v138, 0x4080, v48
	v_mov_b32_e32 v139, v49
	v_lshl_add_u64 v[138:139], v[138:139], 2, s[22:23]
	global_load_dword v158, v[138:139], off
	v_add_u32_e32 v138, 0x8080, v48
	v_mov_b32_e32 v139, v49
	v_lshl_add_u64 v[138:139], v[138:139], 2, s[22:23]
	global_load_dword v143, v[138:139], off
	v_add_u32_e32 v138, 0xc080, v48
	v_mov_b32_e32 v139, v49
	v_lshl_add_u64 v[138:139], v[138:139], 2, s[22:23]
	global_load_dword v159, v[138:139], off
	v_add_u32_e32 v138, 0x90, v48
	v_mov_b32_e32 v139, v49
	v_lshl_add_u64 v[138:139], v[138:139], 2, s[22:23]
	global_load_dword v144, v[138:139], off
	v_add_u32_e32 v138, 0x4090, v48
	v_mov_b32_e32 v139, v49
	v_lshl_add_u64 v[138:139], v[138:139], 2, s[22:23]
	global_load_dword v160, v[138:139], off
	v_add_u32_e32 v138, 0x8090, v48
	v_mov_b32_e32 v139, v49
	v_lshl_add_u64 v[138:139], v[138:139], 2, s[22:23]
	global_load_dword v145, v[138:139], off
	v_add_u32_e32 v138, 0xc090, v48
	v_mov_b32_e32 v139, v49
	v_lshl_add_u64 v[138:139], v[138:139], 2, s[22:23]
	global_load_dword v161, v[138:139], off
	v_add_u32_e32 v138, 0xa0, v48
	v_mov_b32_e32 v139, v49
	v_mov_b32_e32 v141, v49
	v_lshl_add_u64 v[138:139], v[138:139], 2, s[22:23]
	v_lshl_add_u64 v[140:141], v[140:141], 2, s[22:23]
	global_load_dword v138, v[138:139], off
	v_add_u32_e32 v178, 0x80b0, v48
	global_load_dword v139, v[140:141], off
	v_add_u32_e32 v140, 0xc0a0, v48
	v_mov_b32_e32 v141, v49
	v_lshl_add_u64 v[140:141], v[140:141], 2, s[22:23]
	global_load_dword v153, v[140:141], off
	v_add_u32_e32 v140, 0xb0, v48
	v_mov_b32_e32 v141, v49
	v_mov_b32_e32 v179, v49
	v_lshl_add_u64 v[140:141], v[140:141], 2, s[22:23]
	v_lshl_add_u64 v[178:179], v[178:179], 2, s[22:23]
	v_add_u32_e32 v48, 0xc0b0, v48
	global_load_dword v140, v[140:141], off
	s_waitcnt vmcnt(0)
	v_pk_add_f32 v[168:169], v[168:169], v[170:171]
	global_load_dword v141, v[178:179], off
	v_lshl_add_u64 v[178:179], v[48:49], 2, s[22:23]
	global_load_dword v157, v[178:179], off
	v_and_b32_e32 v178, 64, v205
	v_xor_b32_e32 v48, 16, v205
	v_add_u32_e32 v178, 64, v178
	v_cmp_lt_i32_e32 vcc, v48, v178
	v_pk_add_f32 v[150:151], v[150:151], v[166:167]
	s_mov_b32 s6, 0x358637bd
	v_cndmask_b32_e32 v48, v205, v48, vcc
	v_lshlrev_b32_e32 v178, 2, v48
	v_add_f32_e32 v48, v168, v169
	ds_bpermute_b32 v168, v178, v48
	v_pk_add_f32 v[146:147], v[146:147], v[162:163]
	v_mov_b64_e32 v[166:167], s[6:7]
	v_add_f32_e32 v146, v146, v147
	ds_bpermute_b32 v147, v178, v146
	s_waitcnt lgkmcnt(1)
	v_add_f32_e32 v169, v48, v168
	v_add_f32_e32 v48, v150, v151
	ds_bpermute_b32 v150, v178, v48
	v_mov_b32_e32 v171, v169
	s_waitcnt lgkmcnt(1)
	v_add_f32_e32 v147, v146, v147
	v_permlane32_swap_b32_e32 v169, v171
	s_waitcnt lgkmcnt(0)
	v_add_f32_e32 v168, v48, v150
	v_mov_b32_e32 v170, v168
	s_nop 1
	v_permlane32_swap_b32_e32 v168, v170
	v_pk_add_f32 v[148:149], v[148:149], v[164:165]
	v_pk_add_f32 v[150:151], v[168:169], v[170:171]
	v_add_f32_e32 v146, v148, v149
	v_pk_fma_f32 v[168:169], v[150:151], s[36:37], v[166:167] op_sel_hi:[1,0,0]
	v_mov_b32_e32 v163, v147
	v_mul_f32_e32 v48, 0x4b800000, v169
	v_cmp_gt_f32_e64 s[38:39], s75, v169
	s_waitcnt lgkmcnt(0)
	v_mov_b32_e32 v148, v146
	s_nop 1
	v_permlane16_swap_b32_e32 v146, v148
	v_add_f32_e32 v146, v146, v148
	v_mov_b32_e32 v162, v146
	v_cndmask_b32_e64 v48, v169, v48, s[38:39]
	v_rsq_f32_e32 v48, v48
	v_permlane32_swap_b32_e32 v147, v163
	v_permlane32_swap_b32_e32 v146, v162
	v_pk_add_f32 v[142:143], v[142:143], v[158:159]
	v_pk_add_f32 v[146:147], v[146:147], v[162:163]
	v_add_f32_e32 v142, v142, v143
	v_mul_f32_e32 v150, 0x45800000, v48
	v_pk_fma_f32 v[146:147], v[146:147], s[36:37], v[166:167] op_sel_hi:[1,0,0]
	v_cmp_gt_f32_e32 vcc, s75, v168
	v_cndmask_b32_e64 v150, v48, v150, s[38:39]
	s_waitcnt lgkmcnt(0)
	v_mov_b32_e32 v143, v142
	s_nop 1
	v_permlane16_swap_b32_e32 v142, v143
	v_add_f32_e32 v143, v142, v143
	v_mul_f32_e32 v48, 0x4b800000, v168
	v_mul_f32_e32 v148, 0x4b800000, v147
	v_cmp_gt_f32_e64 s[38:39], s75, v147
	v_cndmask_b32_e32 v48, v168, v48, vcc
	v_rsq_f32_e32 v48, v48
	v_cndmask_b32_e64 v147, v147, v148, s[38:39]
	v_pk_add_f32 v[144:145], v[144:145], v[160:161]
	v_rsq_f32_e32 v147, v147
	v_add_f32_e32 v142, v144, v145
	v_mov_b32_e32 v159, v143
	s_nop 1
	v_permlane32_swap_b32_e32 v143, v159
	v_mul_f32_e32 v151, 0x45800000, v48
	s_waitcnt lgkmcnt(0)
	v_mov_b32_e32 v144, v142
	s_nop 1
	v_permlane16_swap_b32_e32 v142, v144
	v_add_f32_e32 v142, v142, v144
	v_mov_b32_e32 v158, v142
	s_nop 1
	v_permlane32_swap_b32_e32 v142, v158
	v_pk_add_f32 v[138:139], v[138:139], v[152:153]
	v_pk_add_f32 v[142:143], v[142:143], v[158:159]
	v_add_f32_e32 v138, v138, v139
	v_mul_f32_e32 v148, 0x45800000, v147
	v_pk_fma_f32 v[142:143], v[142:143], s[36:37], v[166:167] op_sel_hi:[1,0,0]
	v_cndmask_b32_e32 v48, v48, v151, vcc
	v_cmp_gt_f32_e32 vcc, s75, v146
	s_waitcnt lgkmcnt(0)
	v_mov_b32_e32 v139, v138
	s_nop 1
	v_permlane16_swap_b32_e32 v138, v139
	v_add_f32_e32 v139, v138, v139
	v_cndmask_b32_e64 v148, v147, v148, s[38:39]
	v_mul_f32_e32 v147, 0x4b800000, v146
	s_waitcnt vmcnt(0)
	v_pk_add_f32 v[140:141], v[140:141], v[156:157]
	v_mul_f32_e32 v144, 0x4b800000, v143
	v_add_f32_e32 v138, v140, v141
	v_cmp_gt_f32_e64 s[38:39], s75, v143
	v_cndmask_b32_e32 v146, v146, v147, vcc
	v_rsq_f32_e32 v146, v146
	v_cndmask_b32_e64 v143, v143, v144, s[38:39]
	v_rsq_f32_e32 v143, v143
	s_waitcnt lgkmcnt(0)
	v_mov_b32_e32 v140, v138
	s_nop 1
	v_permlane16_swap_b32_e32 v138, v140
	v_add_f32_e32 v138, v138, v140
	v_mov_b32_e32 v153, v139
	v_mov_b32_e32 v152, v138
	s_nop 0
	v_permlane32_swap_b32_e32 v139, v153
	v_permlane32_swap_b32_e32 v138, v152
	v_pk_add_f32 v[138:139], v[138:139], v[152:153]
	v_mul_f32_e32 v147, 0x45800000, v146
	v_mul_f32_e32 v144, 0x45800000, v143
	v_pk_fma_f32 v[138:139], v[138:139], s[36:37], v[166:167] op_sel_hi:[1,0,0]
	v_cndmask_b32_e32 v146, v146, v147, vcc
	v_cmp_gt_f32_e32 vcc, s75, v142
	v_cndmask_b32_e64 v144, v143, v144, s[38:39]
	v_mul_f32_e32 v143, 0x4b800000, v142
	v_mul_f32_e32 v140, 0x4b800000, v139
	v_cmp_gt_f32_e64 s[38:39], s75, v139
	v_cndmask_b32_e32 v142, v142, v143, vcc
	v_rsq_f32_e32 v142, v142
	v_cndmask_b32_e64 v139, v139, v140, s[38:39]
	v_rsq_f32_e32 v139, v139
	s_nop 0
	v_mul_f32_e32 v143, 0x45800000, v142
	v_cndmask_b32_e32 v142, v142, v143, vcc
	v_mul_f32_e32 v140, 0x45800000, v139
	v_cmp_gt_f32_e32 vcc, s75, v138
	v_cndmask_b32_e64 v140, v139, v140, s[38:39]
	v_mul_f32_e32 v139, 0x4b800000, v138
	v_cndmask_b32_e32 v138, v138, v139, vcc
	v_rsq_f32_e32 v138, v138
	s_nop 0
	s_nop 0
	s_nop 0
	v_mul_f32_e32 v139, 0x45800000, v138
	v_cndmask_b32_e32 v138, v138, v139, vcc
	v_mov_b32_e32 v236, v150
	v_mov_b32_e32 v237, v48
	v_mov_b32_e32 v238, v148
	v_mov_b32_e32 v239, v146
	v_mov_b32_e32 v240, v144
	v_mov_b32_e32 v241, v142
	v_mov_b32_e32 v242, v140
	v_mov_b32_e32 v243, v138
	v_writelane_b32 v244, s20, 0
	s_branch .Lrs_done1
.Lrs_hit1:
	v_mov_b32_e32 v150, v236
	v_mov_b32_e32 v48, v237
	v_mov_b32_e32 v148, v238
	v_mov_b32_e32 v146, v239
	v_mov_b32_e32 v144, v240
	v_mov_b32_e32 v142, v241
	v_mov_b32_e32 v140, v242
	v_mov_b32_e32 v138, v243
.Lrs_done1:
	v_pk_mul_f32 v[126:127], v[126:127], v[150:151] op_sel_hi:[1,0]
	v_pk_mul_f32 v[122:123], v[122:123], v[150:151] op_sel_hi:[1,0]
	v_pk_mul_f32 v[124:125], v[124:125], v[150:151] op_sel_hi:[1,0]
	v_pk_mul_f32 v[122:123], v[126:127], v[122:123]
	v_mul_f32_e32 v139, 0xbfb8aa3b, v126
	v_mul_f32_e32 v126, 0xbfb8aa3b, v127
	v_exp_f32_e32 v126, v126
	v_exp_f32_e32 v139, v139
	v_pk_mul_f32 v[118:119], v[118:119], v[150:151] op_sel_hi:[1,0]
	v_pk_mul_f32 v[114:115], v[114:115], v[150:151] op_sel_hi:[1,0]
	v_add_f32_e32 v126, 1.0, v126
	v_rcp_f32_e32 v157, v126
	v_pk_mul_f32 v[126:127], v[128:129], v[150:151] op_sel_hi:[1,0]
	v_add_f32_e32 v139, 1.0, v139
	v_mul_f32_e32 v128, 0xbfb8aa3b, v126
	v_pk_mul_f32 v[124:125], v[126:127], v[124:125]
	v_mul_f32_e32 v126, 0xbfb8aa3b, v127
	v_exp_f32_e32 v128, v128
	v_exp_f32_e32 v126, v126
	v_rcp_f32_e32 v156, v139
	v_pk_mul_f32 v[114:115], v[118:119], v[114:115]
	v_add_f32_e32 v128, 1.0, v128
	v_add_f32_e32 v126, 1.0, v126
	v_rcp_f32_e32 v128, v128
	v_rcp_f32_e32 v129, v126
	v_pk_mul_f32 v[122:123], v[122:123], v[156:157]
	v_pk_mul_f32 v[116:117], v[116:117], v[150:151] op_sel_hi:[1,0]
	v_cvt_pk_bf16_f32 v122, v122, v123
	v_pk_mul_f32 v[124:125], v[124:125], v[128:129]
	v_lshl_or_b32 v152, s18, 7, v175
	v_cvt_pk_bf16_f32 v123, v124, v125
	v_mul_f32_e32 v124, 0xbfb8aa3b, v118
	v_mul_f32_e32 v118, 0xbfb8aa3b, v119
	v_exp_f32_e32 v118, v118
	v_exp_f32_e32 v124, v124
	s_movk_i32 s6, 0xb00
	v_pk_mul_f32 v[110:111], v[110:111], v[48:49] op_sel_hi:[1,0]
	v_add_f32_e32 v118, 1.0, v118
	v_rcp_f32_e32 v125, v118
	v_pk_mul_f32 v[118:119], v[120:121], v[150:151] op_sel_hi:[1,0]
	v_add_f32_e32 v124, 1.0, v124
	v_mul_f32_e32 v120, 0xbfb8aa3b, v118
	v_pk_mul_f32 v[116:117], v[118:119], v[116:117]
	v_mul_f32_e32 v118, 0xbfb8aa3b, v119
	v_exp_f32_e32 v120, v120
	v_exp_f32_e32 v118, v118
	v_rcp_f32_e32 v124, v124
	v_pk_mul_f32 v[106:107], v[106:107], v[48:49] op_sel_hi:[1,0]
	v_add_f32_e32 v120, 1.0, v120
	v_add_f32_e32 v118, 1.0, v118
	v_rcp_f32_e32 v120, v120
	v_rcp_f32_e32 v121, v118
	v_pk_mul_f32 v[114:115], v[114:115], v[124:125]
	v_pk_mul_f32 v[106:107], v[110:111], v[106:107]
	v_cvt_pk_bf16_f32 v124, v114, v115
	v_mad_u64_u32 v[114:115], s[20:21], v177, s6, v[152:153]
	v_pk_mul_f32 v[116:117], v[116:117], v[120:121]
	v_mov_b32_e32 v115, v49
	v_cvt_pk_bf16_f32 v125, v116, v117
	v_lshl_add_u64 v[116:117], v[114:115], 1, s[12:13]
	v_mul_f32_e32 v115, 0xbfb8aa3b, v110
	v_mul_f32_e32 v110, 0xbfb8aa3b, v111
	v_exp_f32_e32 v110, v110
	global_store_dwordx4 v[116:117], v[122:125], off
	s_nop 1
	v_pk_mul_f32 v[108:109], v[108:109], v[48:49] op_sel_hi:[1,0]
	v_exp_f32_e32 v115, v115
	v_add_f32_e32 v110, 1.0, v110
	v_rcp_f32_e32 v117, v110
	v_pk_mul_f32 v[110:111], v[112:113], v[48:49] op_sel_hi:[1,0]
	v_add_f32_e32 v115, 1.0, v115
	v_mul_f32_e32 v112, 0xbfb8aa3b, v110
	v_pk_mul_f32 v[108:109], v[110:111], v[108:109]
	v_mul_f32_e32 v110, 0xbfb8aa3b, v111
	v_exp_f32_e32 v112, v112
	v_exp_f32_e32 v110, v110
	v_rcp_f32_e32 v116, v115
	v_pk_mul_f32 v[102:103], v[102:103], v[48:49] op_sel_hi:[1,0]
	v_add_f32_e32 v112, 1.0, v112
	v_add_f32_e32 v110, 1.0, v110
	v_rcp_f32_e32 v112, v112
	v_rcp_f32_e32 v113, v110
	v_pk_mul_f32 v[106:107], v[106:107], v[116:117]
	v_pk_mul_f32 v[98:99], v[98:99], v[48:49] op_sel_hi:[1,0]
	v_cvt_pk_bf16_f32 v106, v106, v107
	v_pk_mul_f32 v[108:109], v[108:109], v[112:113]
	v_pk_mul_f32 v[98:99], v[102:103], v[98:99]
	v_cvt_pk_bf16_f32 v107, v108, v109
	v_mul_f32_e32 v108, 0xbfb8aa3b, v102
	v_mul_f32_e32 v102, 0xbfb8aa3b, v103
	v_exp_f32_e32 v102, v102
	v_exp_f32_e32 v108, v108
	v_pk_mul_f32 v[100:101], v[100:101], v[48:49] op_sel_hi:[1,0]
	v_pk_mul_f32 v[94:95], v[94:95], v[148:149] op_sel_hi:[1,0]
	v_add_f32_e32 v102, 1.0, v102
	v_rcp_f32_e32 v109, v102
	v_pk_mul_f32 v[102:103], v[104:105], v[48:49] op_sel_hi:[1,0]
	v_add_f32_e32 v108, 1.0, v108
	v_mul_f32_e32 v48, 0xbfb8aa3b, v103
	v_exp_f32_e32 v48, v48
	v_rcp_f32_e32 v108, v108
	v_mul_f32_e32 v104, 0xbfb8aa3b, v102
	v_exp_f32_e32 v104, v104
	v_add_f32_e32 v48, 1.0, v48
	v_pk_mul_f32 v[98:99], v[98:99], v[108:109]
	v_rcp_f32_e32 v105, v48
	v_add_u32_e32 v48, 0xb000, v114
	v_add_f32_e32 v104, 1.0, v104
	v_cvt_pk_bf16_f32 v108, v98, v99
	v_lshl_add_u64 v[98:99], v[48:49], 1, s[12:13]
	v_mul_f32_e32 v48, 0xbfb8aa3b, v94
	v_rcp_f32_e32 v104, v104
	v_exp_f32_e32 v48, v48
	v_pk_mul_f32 v[100:101], v[102:103], v[100:101]
	v_pk_mul_f32 v[90:91], v[90:91], v[148:149] op_sel_hi:[1,0]
	v_pk_mul_f32 v[100:101], v[100:101], v[104:105]
	v_add_f32_e32 v48, 1.0, v48
	v_cvt_pk_bf16_f32 v109, v100, v101
	global_store_dwordx4 v[98:99], v[106:109], off
	s_nop 1
	v_rcp_f32_e32 v98, v48
	v_mul_f32_e32 v48, 0xbfb8aa3b, v95
	v_exp_f32_e32 v48, v48
	v_pk_mul_f32 v[90:91], v[94:95], v[90:91]
	v_pk_mul_f32 v[94:95], v[96:97], v[148:149] op_sel_hi:[1,0]
	v_pk_mul_f32 v[86:87], v[86:87], v[148:149] op_sel_hi:[1,0]
	v_add_f32_e32 v48, 1.0, v48
	v_rcp_f32_e32 v99, v48
	v_mul_f32_e32 v48, 0xbfb8aa3b, v94
	v_exp_f32_e32 v48, v48
	v_pk_mul_f32 v[92:93], v[92:93], v[148:149] op_sel_hi:[1,0]
	v_pk_mul_f32 v[90:91], v[90:91], v[98:99]
	v_pk_mul_f32 v[92:93], v[94:95], v[92:93]
	v_add_f32_e32 v48, 1.0, v48
	v_rcp_f32_e32 v96, v48
	v_mul_f32_e32 v48, 0xbfb8aa3b, v95
	v_exp_f32_e32 v48, v48
	v_cvt_pk_bf16_f32 v90, v90, v91
	v_pk_mul_f32 v[82:83], v[82:83], v[148:149] op_sel_hi:[1,0]
	v_pk_mul_f32 v[78:79], v[78:79], v[146:147] op_sel_hi:[1,0]
	v_add_f32_e32 v48, 1.0, v48
	v_rcp_f32_e32 v97, v48
	v_mul_f32_e32 v48, 0xbfb8aa3b, v86
	v_exp_f32_e32 v48, v48
	v_pk_mul_f32 v[82:83], v[86:87], v[82:83]
	v_pk_mul_f32 v[92:93], v[92:93], v[96:97]
	v_pk_mul_f32 v[84:85], v[84:85], v[148:149] op_sel_hi:[1,0]
	v_add_f32_e32 v48, 1.0, v48
	v_cvt_pk_bf16_f32 v91, v92, v93
	v_rcp_f32_e32 v92, v48
	v_mul_f32_e32 v48, 0xbfb8aa3b, v87
	v_exp_f32_e32 v48, v48
	v_pk_mul_f32 v[86:87], v[88:89], v[148:149] op_sel_hi:[1,0]
	v_pk_mul_f32 v[74:75], v[74:75], v[146:147] op_sel_hi:[1,0]
	v_pk_mul_f32 v[84:85], v[86:87], v[84:85]
	v_add_f32_e32 v48, 1.0, v48
	v_rcp_f32_e32 v93, v48
	v_mul_f32_e32 v48, 0xbfb8aa3b, v86
	v_exp_f32_e32 v48, v48
	v_pk_mul_f32 v[74:75], v[78:79], v[74:75]
	v_pk_mul_f32 v[82:83], v[82:83], v[92:93]
	v_pk_mul_f32 v[70:71], v[70:71], v[146:147] op_sel_hi:[1,0]
	v_add_f32_e32 v48, 1.0, v48
	v_rcp_f32_e32 v88, v48
	v_mul_f32_e32 v48, 0xbfb8aa3b, v87
	v_exp_f32_e32 v48, v48
	v_cvt_pk_bf16_f32 v92, v82, v83
	v_pk_mul_f32 v[76:77], v[76:77], v[146:147] op_sel_hi:[1,0]
	v_pk_mul_f32 v[66:67], v[66:67], v[146:147] op_sel_hi:[1,0]
	v_add_f32_e32 v48, 1.0, v48
	v_rcp_f32_e32 v89, v48
	v_add_u32_e32 v48, 0x16000, v114
	v_lshl_add_u64 v[82:83], v[48:49], 1, s[12:13]
	v_mul_f32_e32 v48, 0xbfb8aa3b, v78
	v_exp_f32_e32 v48, v48
	v_pk_mul_f32 v[84:85], v[84:85], v[88:89]
	v_pk_mul_f32 v[66:67], v[70:71], v[66:67]
	v_cvt_pk_bf16_f32 v93, v84, v85
	v_add_f32_e32 v48, 1.0, v48
	global_store_dwordx4 v[82:83], v[90:93], off
	s_nop 1
	v_rcp_f32_e32 v82, v48
	v_mul_f32_e32 v48, 0xbfb8aa3b, v79
	v_exp_f32_e32 v48, v48
	v_pk_mul_f32 v[78:79], v[80:81], v[146:147] op_sel_hi:[1,0]
	v_pk_mul_f32 v[62:63], v[62:63], v[144:145] op_sel_hi:[1,0]
	v_pk_mul_f32 v[76:77], v[78:79], v[76:77]
	v_add_f32_e32 v48, 1.0, v48
	v_rcp_f32_e32 v83, v48
	v_mul_f32_e32 v48, 0xbfb8aa3b, v78
	v_exp_f32_e32 v48, v48
	v_pk_mul_f32 v[68:69], v[68:69], v[146:147] op_sel_hi:[1,0]
	v_pk_mul_f32 v[74:75], v[74:75], v[82:83]
	v_pk_mul_f32 v[58:59], v[58:59], v[144:145] op_sel_hi:[1,0]
	v_add_f32_e32 v48, 1.0, v48
	v_rcp_f32_e32 v80, v48
	v_mul_f32_e32 v48, 0xbfb8aa3b, v79
	v_exp_f32_e32 v48, v48
	v_cvt_pk_bf16_f32 v74, v74, v75
	v_pk_mul_f32 v[58:59], v[62:63], v[58:59]
	v_pk_mul_f32 v[54:55], v[54:55], v[144:145] op_sel_hi:[1,0]
	v_add_f32_e32 v48, 1.0, v48
	v_rcp_f32_e32 v81, v48
	v_mul_f32_e32 v48, 0xbfb8aa3b, v70
	v_exp_f32_e32 v48, v48
	v_pk_mul_f32 v[60:61], v[60:61], v[144:145] op_sel_hi:[1,0]
	v_pk_mul_f32 v[76:77], v[76:77], v[80:81]
	v_pk_mul_f32 v[50:51], v[50:51], v[144:145] op_sel_hi:[1,0]
	v_add_f32_e32 v48, 1.0, v48
	v_cvt_pk_bf16_f32 v75, v76, v77
	v_rcp_f32_e32 v76, v48
	v_mul_f32_e32 v48, 0xbfb8aa3b, v71
	v_exp_f32_e32 v48, v48
	v_pk_mul_f32 v[70:71], v[72:73], v[146:147] op_sel_hi:[1,0]
	v_pk_mul_f32 v[50:51], v[54:55], v[50:51]
	v_pk_mul_f32 v[68:69], v[70:71], v[68:69]
	v_add_f32_e32 v48, 1.0, v48
	v_rcp_f32_e32 v77, v48
	v_mul_f32_e32 v48, 0xbfb8aa3b, v70
	v_exp_f32_e32 v48, v48
	v_pk_mul_f32 v[44:45], v[44:45], v[142:143] op_sel_hi:[1,0]
	v_pk_mul_f32 v[66:67], v[66:67], v[76:77]
	v_pk_mul_f32 v[40:41], v[40:41], v[142:143] op_sel_hi:[1,0]
	v_add_f32_e32 v48, 1.0, v48
	v_rcp_f32_e32 v72, v48
	v_mul_f32_e32 v48, 0xbfb8aa3b, v71
	v_exp_f32_e32 v48, v48
	v_cvt_pk_bf16_f32 v76, v66, v67
	v_pk_mul_f32 v[40:41], v[44:45], v[40:41]
	v_pk_mul_f32 v[52:53], v[52:53], v[144:145] op_sel_hi:[1,0]
	v_add_f32_e32 v48, 1.0, v48
	v_rcp_f32_e32 v73, v48
	v_add_u32_e32 v48, 0x21000, v114
	v_lshl_add_u64 v[66:67], v[48:49], 1, s[12:13]
	v_mul_f32_e32 v48, 0xbfb8aa3b, v62
	v_exp_f32_e32 v48, v48
	v_pk_mul_f32 v[68:69], v[68:69], v[72:73]
	v_pk_mul_f32 v[42:43], v[42:43], v[142:143] op_sel_hi:[1,0]
	v_cvt_pk_bf16_f32 v77, v68, v69
	v_add_f32_e32 v48, 1.0, v48
	global_store_dwordx4 v[66:67], v[74:77], off
	s_nop 1
	v_rcp_f32_e32 v66, v48
	v_mul_f32_e32 v48, 0xbfb8aa3b, v63
	v_exp_f32_e32 v48, v48
	v_pk_mul_f32 v[62:63], v[64:65], v[144:145] op_sel_hi:[1,0]
	v_pk_mul_f32 v[36:37], v[36:37], v[142:143] op_sel_hi:[1,0]
	v_pk_mul_f32 v[60:61], v[62:63], v[60:61]
	v_add_f32_e32 v48, 1.0, v48
	v_rcp_f32_e32 v67, v48
	v_mul_f32_e32 v48, 0xbfb8aa3b, v62
	v_exp_f32_e32 v48, v48
	v_pk_mul_f32 v[32:33], v[32:33], v[142:143] op_sel_hi:[1,0]
	v_pk_mul_f32 v[58:59], v[58:59], v[66:67]
	v_pk_mul_f32 v[32:33], v[36:37], v[32:33]
	v_add_f32_e32 v48, 1.0, v48
	v_rcp_f32_e32 v64, v48
	v_mul_f32_e32 v48, 0xbfb8aa3b, v63
	v_exp_f32_e32 v48, v48
	v_cvt_pk_bf16_f32 v58, v58, v59
	v_pk_mul_f32 v[34:35], v[34:35], v[142:143] op_sel_hi:[1,0]
	v_pk_mul_f32 v[28:29], v[28:29], v[140:141] op_sel_hi:[1,0]
	v_add_f32_e32 v48, 1.0, v48
	v_rcp_f32_e32 v65, v48
	v_mul_f32_e32 v48, 0xbfb8aa3b, v54
	v_exp_f32_e32 v48, v48
	v_pk_mul_f32 v[24:25], v[24:25], v[140:141] op_sel_hi:[1,0]
	v_pk_mul_f32 v[60:61], v[60:61], v[64:65]
	v_pk_mul_f32 v[24:25], v[28:29], v[24:25]
	v_add_f32_e32 v48, 1.0, v48
	v_cvt_pk_bf16_f32 v59, v60, v61
	v_rcp_f32_e32 v60, v48
	v_mul_f32_e32 v48, 0xbfb8aa3b, v55
	v_exp_f32_e32 v48, v48
	v_pk_mul_f32 v[54:55], v[56:57], v[144:145] op_sel_hi:[1,0]
	v_pk_mul_f32 v[26:27], v[26:27], v[140:141] op_sel_hi:[1,0]
	v_pk_mul_f32 v[52:53], v[54:55], v[52:53]
	v_add_f32_e32 v48, 1.0, v48
	v_rcp_f32_e32 v61, v48
	v_mul_f32_e32 v48, 0xbfb8aa3b, v54
	v_exp_f32_e32 v48, v48
	v_pk_mul_f32 v[20:21], v[20:21], v[140:141] op_sel_hi:[1,0]
	v_pk_mul_f32 v[50:51], v[50:51], v[60:61]
	v_pk_mul_f32 v[16:17], v[16:17], v[140:141] op_sel_hi:[1,0]
	v_add_f32_e32 v48, 1.0, v48
	v_rcp_f32_e32 v56, v48
	v_mul_f32_e32 v48, 0xbfb8aa3b, v55
	v_exp_f32_e32 v48, v48
	v_cvt_pk_bf16_f32 v60, v50, v51
	v_pk_mul_f32 v[16:17], v[20:21], v[16:17]
	v_pk_mul_f32 v[18:19], v[18:19], v[140:141] op_sel_hi:[1,0]
	v_add_f32_e32 v48, 1.0, v48
	v_rcp_f32_e32 v57, v48
	v_add_u32_e32 v48, 0x58000, v114
	v_lshl_add_u64 v[50:51], v[48:49], 1, s[12:13]
	v_mul_f32_e32 v48, 0xbfb8aa3b, v44
	v_mul_f32_e32 v44, 0xbfb8aa3b, v45
	v_exp_f32_e32 v44, v44
	v_pk_mul_f32 v[52:53], v[52:53], v[56:57]
	v_exp_f32_e32 v48, v48
	v_cvt_pk_bf16_f32 v61, v52, v53
	v_add_f32_e32 v44, 1.0, v44
	global_store_dwordx4 v[50:51], v[58:61], off
	s_nop 1
	v_rcp_f32_e32 v51, v44
	v_pk_mul_f32 v[44:45], v[46:47], v[142:143] op_sel_hi:[1,0]
	v_add_f32_e32 v48, 1.0, v48
	v_mul_f32_e32 v46, 0xbfb8aa3b, v44
	v_pk_mul_f32 v[42:43], v[44:45], v[42:43]
	v_mul_f32_e32 v44, 0xbfb8aa3b, v45
	v_exp_f32_e32 v46, v46
	v_exp_f32_e32 v44, v44
	v_rcp_f32_e32 v50, v48
	v_add_u32_e32 v48, 0x63000, v114
	v_add_f32_e32 v46, 1.0, v46
	v_add_f32_e32 v44, 1.0, v44
	v_rcp_f32_e32 v46, v46
	v_rcp_f32_e32 v47, v44
	v_pk_mul_f32 v[40:41], v[40:41], v[50:51]
	v_pk_mul_f32 v[12:13], v[12:13], v[138:139] op_sel_hi:[1,0]
	v_cvt_pk_bf16_f32 v40, v40, v41
	v_pk_mul_f32 v[42:43], v[42:43], v[46:47]
	v_pk_mul_f32 v[8:9], v[8:9], v[138:139] op_sel_hi:[1,0]
	v_cvt_pk_bf16_f32 v41, v42, v43
	v_mul_f32_e32 v42, 0xbfb8aa3b, v36
	v_mul_f32_e32 v36, 0xbfb8aa3b, v37
	v_exp_f32_e32 v36, v36
	v_exp_f32_e32 v42, v42
	v_pk_mul_f32 v[8:9], v[12:13], v[8:9]
	v_pk_mul_f32 v[10:11], v[10:11], v[138:139] op_sel_hi:[1,0]
	v_add_f32_e32 v36, 1.0, v36
	v_rcp_f32_e32 v43, v36
	v_pk_mul_f32 v[36:37], v[38:39], v[142:143] op_sel_hi:[1,0]
	v_add_f32_e32 v42, 1.0, v42
	v_mul_f32_e32 v38, 0xbfb8aa3b, v36
	v_pk_mul_f32 v[34:35], v[36:37], v[34:35]
	v_mul_f32_e32 v36, 0xbfb8aa3b, v37
	v_exp_f32_e32 v38, v38
	v_exp_f32_e32 v36, v36
	v_rcp_f32_e32 v42, v42
	v_pk_mul_f32 v[4:5], v[4:5], v[138:139] op_sel_hi:[1,0]
	v_add_f32_e32 v38, 1.0, v38
	v_add_f32_e32 v36, 1.0, v36
	v_rcp_f32_e32 v38, v38
	v_rcp_f32_e32 v39, v36
	v_pk_mul_f32 v[32:33], v[32:33], v[42:43]
	v_pk_mul_f32 v[0:1], v[0:1], v[138:139] op_sel_hi:[1,0]
	v_cvt_pk_bf16_f32 v42, v32, v33
	v_pk_mul_f32 v[34:35], v[34:35], v[38:39]
	v_lshl_add_u64 v[32:33], v[48:49], 1, s[12:13]
	v_cvt_pk_bf16_f32 v43, v34, v35
	global_store_dwordx4 v[32:33], v[40:43], off
	s_nop 1
	v_mul_f32_e32 v32, 0xbfb8aa3b, v28
	v_mul_f32_e32 v28, 0xbfb8aa3b, v29
	v_exp_f32_e32 v28, v28
	v_exp_f32_e32 v32, v32
	v_add_u32_e32 v48, 0x6e000, v114
	v_pk_mul_f32 v[0:1], v[4:5], v[0:1]
	v_add_f32_e32 v28, 1.0, v28
	v_rcp_f32_e32 v33, v28
	v_pk_mul_f32 v[28:29], v[30:31], v[140:141] op_sel_hi:[1,0]
	v_add_f32_e32 v32, 1.0, v32
	v_mul_f32_e32 v30, 0xbfb8aa3b, v28
	v_pk_mul_f32 v[26:27], v[28:29], v[26:27]
	v_mul_f32_e32 v28, 0xbfb8aa3b, v29
	v_exp_f32_e32 v30, v30
	v_exp_f32_e32 v28, v28
	v_rcp_f32_e32 v32, v32
	v_pk_mul_f32 v[2:3], v[2:3], v[138:139] op_sel_hi:[1,0]
	v_add_f32_e32 v30, 1.0, v30
	v_add_f32_e32 v28, 1.0, v28
	v_rcp_f32_e32 v30, v30
	v_rcp_f32_e32 v31, v28
	v_pk_mul_f32 v[24:25], v[24:25], v[32:33]
	s_mov_b64 s[38:39], -1
	v_cvt_pk_bf16_f32 v24, v24, v25
	v_pk_mul_f32 v[26:27], v[26:27], v[30:31]
	s_andn2_b64 vcc, exec, s[48:49]
	v_cvt_pk_bf16_f32 v25, v26, v27
	v_mul_f32_e32 v26, 0xbfb8aa3b, v20
	v_mul_f32_e32 v20, 0xbfb8aa3b, v21
	v_exp_f32_e32 v20, v20
	v_exp_f32_e32 v26, v26
	v_add_f32_e32 v20, 1.0, v20
	v_rcp_f32_e32 v27, v20
	v_pk_mul_f32 v[20:21], v[22:23], v[140:141] op_sel_hi:[1,0]
	v_add_f32_e32 v26, 1.0, v26
	v_mul_f32_e32 v22, 0xbfb8aa3b, v20
	v_pk_mul_f32 v[18:19], v[20:21], v[18:19]
	v_mul_f32_e32 v20, 0xbfb8aa3b, v21
	v_exp_f32_e32 v22, v22
	v_exp_f32_e32 v20, v20
	v_rcp_f32_e32 v26, v26
	v_add_f32_e32 v22, 1.0, v22
	v_add_f32_e32 v20, 1.0, v20
	v_rcp_f32_e32 v22, v22
	v_rcp_f32_e32 v23, v20
	v_pk_mul_f32 v[16:17], v[16:17], v[26:27]
	v_pk_mul_f32 v[18:19], v[18:19], v[22:23]
	v_cvt_pk_bf16_f32 v26, v16, v17
	v_lshl_add_u64 v[16:17], v[48:49], 1, s[12:13]
	v_cvt_pk_bf16_f32 v27, v18, v19
	global_store_dwordx4 v[16:17], v[24:27], off
	s_nop 1
	v_mul_f32_e32 v16, 0xbfb8aa3b, v12
	v_mul_f32_e32 v12, 0xbfb8aa3b, v13
	v_exp_f32_e32 v12, v12
	v_exp_f32_e32 v16, v16
	v_add_u32_e32 v48, 0x79000, v114
	v_add_f32_e32 v12, 1.0, v12
	v_rcp_f32_e32 v17, v12
	v_pk_mul_f32 v[12:13], v[14:15], v[138:139] op_sel_hi:[1,0]
	v_add_f32_e32 v16, 1.0, v16
	v_mul_f32_e32 v14, 0xbfb8aa3b, v12
	v_pk_mul_f32 v[10:11], v[12:13], v[10:11]
	v_mul_f32_e32 v12, 0xbfb8aa3b, v13
	v_exp_f32_e32 v14, v14
	v_exp_f32_e32 v12, v12
	v_rcp_f32_e32 v16, v16
	v_add_f32_e32 v14, 1.0, v14
	v_add_f32_e32 v12, 1.0, v12
	v_rcp_f32_e32 v14, v14
	v_rcp_f32_e32 v15, v12
	v_pk_mul_f32 v[8:9], v[8:9], v[16:17]
	v_pk_mul_f32 v[10:11], v[10:11], v[14:15]
	v_cvt_pk_bf16_f32 v8, v8, v9
	v_cvt_pk_bf16_f32 v9, v10, v11
	v_mul_f32_e32 v10, 0xbfb8aa3b, v4
	v_mul_f32_e32 v4, 0xbfb8aa3b, v5
	v_exp_f32_e32 v4, v4
	v_exp_f32_e32 v10, v10
	v_add_f32_e32 v4, 1.0, v4
	v_rcp_f32_e32 v11, v4
	v_pk_mul_f32 v[4:5], v[6:7], v[138:139] op_sel_hi:[1,0]
	v_add_f32_e32 v10, 1.0, v10
	v_mul_f32_e32 v6, 0xbfb8aa3b, v4
	v_pk_mul_f32 v[2:3], v[4:5], v[2:3]
	v_mul_f32_e32 v4, 0xbfb8aa3b, v5
	v_exp_f32_e32 v6, v6
	v_exp_f32_e32 v4, v4
	v_rcp_f32_e32 v10, v10
	v_add_f32_e32 v6, 1.0, v6
	v_add_f32_e32 v4, 1.0, v4
	v_rcp_f32_e32 v6, v6
	v_rcp_f32_e32 v7, v4
	v_pk_mul_f32 v[0:1], v[0:1], v[10:11]
	v_pk_mul_f32 v[2:3], v[2:3], v[6:7]
	v_cvt_pk_bf16_f32 v10, v0, v1
	v_cvt_pk_bf16_f32 v11, v2, v3
	v_lshl_add_u64 v[0:1], v[48:49], 1, s[12:13]
	global_store_dwordx4 v[0:1], v[8:11], off
	s_nop 1
	s_cbranch_vccnz .LBB0_244
	s_andn2_b64 vcc, exec, s[40:41]
	s_cbranch_vccnz .LBB0_243
	s_barrier
	s_branch .LBB0_243

.LBB0_1401:
	s_andn2_b64 vcc, exec, s[2:3]
	s_cbranch_vccnz .LBB0_1954
	v_mov_b32_e32 v0, v155
	v_writelane_b32 v244, 0, 0
	v_readlane_b32 s7, v254, 0
	s_waitcnt vmcnt(4)
	v_mov_b32_e32 v14, v155
	s_cmpk_gt_i32 s7, 0x57f
	v_readfirstlane_b32 s33, v14
	s_cbranch_scc1 .LBB0_1418
	v_lshlrev_b32_e32 v0, 4, v14
	v_add_u32_e32 v1, 0x2000, v0
	v_ashrrev_i32_e32 v2, 31, v1
	v_lshrrev_b32_e32 v2, 22, v2
	v_add_u32_e32 v2, v1, v2
	v_ashrrev_i32_e32 v8, 10, v2
	v_mul_i32_i24_e32 v3, 0x400, v8
	v_sub_u32_e32 v1, v1, v3
	v_lshrrev_b32_e32 v3, 4, v1
	v_bitop3_b32 v1, v3, v1, 32 bitop3:0x6c
	v_ashrrev_i32_e32 v3, 31, v1
	v_readlane_b32 s2, v255, 29
	v_lshrrev_b32_e32 v3, 26, v3
	v_readlane_b32 s3, v255, 30
	s_add_u32 s8, s2, 0x1080000
	v_add_u32_e32 v3, v1, v3
	s_addc_u32 s9, s3, 0
	v_ashrrev_i32_e32 v9, 6, v3
	v_and_b32_e32 v3, 0xc0, v3
	s_ashr_i32 s2, s7, 31
	v_sub_u32_e32 v1, v1, v3
	s_lshr_b32 s2, s2, 29
	v_lshlrev_b32_e32 v2, 5, v8
	v_ashrrev_i16_sdwa v1, v204, sext(v1) dst_sel:DWORD dst_unused:UNUSED_PAD src0_sel:DWORD src1_sel:BYTE_0
	s_add_i32 s2, s7, s2
	s_ashr_i32 s40, s33, 6
	v_and_b32_e32 v2, 32, v2
	v_bfe_i32 v10, v1, 0, 16
	s_ashr_i32 s3, s2, 3
	s_and_b32 s2, s2, -8
	s_ashr_i32 s41, s33, 8
	s_lshl_b32 s58, s40, 10
	v_add_u32_e32 v1, v2, v10
	v_lshlrev_b32_e32 v2, 3, v8
	s_sub_i32 s2, s7, s2
	v_and_b32_e32 v2, 0x1ffff0, v2
	s_cmp_lt_i32 s2, 0
	s_movk_i32 s6, 0xb1
	v_add_lshl_u32 v2, v9, v2, 11
	s_cselect_b32 s6, s6, 0xb0
	s_waitcnt vmcnt(1)
	v_lshl_add_u32 v130, v1, 1, v2
	v_bfe_i32 v2, v14, 27, 1
	s_mul_i32 s2, s2, s6
	v_lshrrev_b32_e32 v2, 22, v2
	s_add_i32 s2, s2, s3
	v_add_u32_e32 v2, v0, v2
	s_mul_hi_i32 s3, s2, 0x2e8ba2e9
	v_and_b32_e32 v2, 0xfffffc00, v2
	s_lshr_b32 s6, s3, 31
	s_ashr_i32 s3, s3, 5
	v_sub_u32_e32 v0, v0, v2
	s_add_i32 s3, s3, s6
	v_lshrrev_b32_e32 v2, 4, v0
	s_lshl_b32 s6, s3, 3
	s_mulk_i32 s3, 0xb0
	v_bitop3_b32 v0, v2, v0, 32 bitop3:0x6c
	s_sub_i32 s2, s2, s3
	v_ashrrev_i32_e32 v2, 31, v0
	s_bfe_u32 s3, s2, 0x3001c
	v_ashrrev_i32_e32 v1, 31, v14
	v_lshrrev_b32_e32 v2, 26, v2
	s_add_i32 s3, s2, s3
	v_lshrrev_b32_e32 v1, 26, v1
	v_add_u32_e32 v2, v0, v2
	s_sext_i32_i16 s18, s3
	s_and_b32 s3, s3, 0xfff8
	v_add_u32_e32 v1, v14, v1
	v_ashrrev_i32_e32 v12, 6, v2
	v_and_b32_e32 v2, 0xc0, v2
	s_sub_i32 s2, s2, s3
	v_ashrrev_i32_e32 v11, 6, v1
	v_sub_u32_e32 v0, v0, v2
	s_sext_i32_i16 s2, s2
	v_lshlrev_b32_e32 v1, 5, v11
	v_ashrrev_i16_sdwa v0, v204, sext(v0) dst_sel:DWORD dst_unused:UNUSED_PAD src0_sel:DWORD src1_sel:BYTE_0
	s_lshr_b32 s24, s18, 3
	s_add_i32 s38, s6, s2
	v_and_b32_e32 v1, 32, v1
	v_bfe_i32 v13, v0, 0, 16
	s_ashr_i32 s39, s38, 31
	s_bfe_i64 s[20:21], s[24:25], 0x100000
	v_add_u32_e32 v0, v1, v13
	v_lshlrev_b32_e32 v1, 3, v11
	s_lshl_b64 s[2:3], s[38:39], 19
	s_lshl_b64 s[20:21], s[20:21], 19
	v_and_b32_e32 v1, 0x1ffff0, v1
	s_add_u32 s54, s8, s20
	v_add_lshl_u32 v1, v12, v1, 11
	s_addc_u32 s55, s9, s21
	s_add_i32 s59, s58, 0
	v_lshl_add_u32 v132, v0, 1, v1
	s_add_i32 m0, s59, 0x10000
	v_mov_b32_e32 v133, v49
	global_load_lds_dwordx4 v132, s[54:55]
	s_add_i32 m0, s59, 0x12000
	s_add_u32 s20, s54, 0x40000
	global_load_lds_dwordx4 v130, s[54:55]
	s_addc_u32 s21, s55, 0
	s_add_i32 m0, s59, 0x14000
	v_mov_b32_e32 v131, v49
	global_load_lds_dwordx4 v132, s[20:21]
	s_add_i32 m0, s59, 0x16000
	s_add_u32 s52, s16, s2
	s_addc_u32 s53, s17, s3
	s_add_i32 s60, s59, 0x2000
	global_load_lds_dwordx4 v130, s[20:21]
	s_mov_b32 m0, s59
	s_add_u32 s2, s52, 0x40000
	global_load_lds_dwordx4 v132, s[52:53]
	s_mov_b32 m0, s60
	s_addc_u32 s3, s53, 0
	s_add_i32 s61, s59, 0x4000
	global_load_lds_dwordx4 v130, s[52:53]
	s_mov_b32 m0, s61
	s_add_i32 s62, s59, 0x6000
	global_load_lds_dwordx4 v132, s[2:3]
	s_mov_b32 m0, s62
	s_cmp_eq_u32 s41, 1
	global_load_lds_dwordx4 v130, s[2:3]
	v_lshl_add_u64 v[6:7], s[54:55], 0, v[132:133]
	v_lshl_add_u64 v[4:5], s[54:55], 0, v[130:131]
	v_lshl_add_u64 v[0:1], s[52:53], 0, v[132:133]
	s_cselect_b64 s[2:3], -1, 0
	s_cmp_lg_u32 s41, 1
	v_lshl_add_u64 v[2:3], s[52:53], 0, v[130:131]
	s_cbranch_scc1 .LBB0_1405
	s_barrier

.Lrs_done2:
	v_pk_mul_f32 v[126:127], v[126:127], v[150:151] op_sel_hi:[1,0]
	v_pk_mul_f32 v[122:123], v[122:123], v[150:151] op_sel_hi:[1,0]
	v_pk_mul_f32 v[124:125], v[124:125], v[150:151] op_sel_hi:[1,0]
	v_pk_mul_f32 v[122:123], v[126:127], v[122:123]
	v_mul_f32_e32 v139, 0xbfb8aa3b, v126
	v_mul_f32_e32 v126, 0xbfb8aa3b, v127
	v_exp_f32_e32 v126, v126
	v_exp_f32_e32 v139, v139
	v_pk_mul_f32 v[118:119], v[118:119], v[150:151] op_sel_hi:[1,0]
	v_pk_mul_f32 v[114:115], v[114:115], v[150:151] op_sel_hi:[1,0]
	v_add_f32_e32 v126, 1.0, v126
	v_rcp_f32_e32 v157, v126
	v_pk_mul_f32 v[126:127], v[128:129], v[150:151] op_sel_hi:[1,0]
	v_add_f32_e32 v139, 1.0, v139
	v_mul_f32_e32 v128, 0xbfb8aa3b, v126
	v_pk_mul_f32 v[124:125], v[126:127], v[124:125]
	v_mul_f32_e32 v126, 0xbfb8aa3b, v127
	v_exp_f32_e32 v128, v128
	v_exp_f32_e32 v126, v126
	v_rcp_f32_e32 v156, v139
	v_pk_mul_f32 v[114:115], v[118:119], v[114:115]
	v_add_f32_e32 v128, 1.0, v128
	v_add_f32_e32 v126, 1.0, v126
	v_rcp_f32_e32 v128, v128
	v_rcp_f32_e32 v129, v126
	v_pk_mul_f32 v[122:123], v[122:123], v[156:157]
	v_pk_mul_f32 v[116:117], v[116:117], v[150:151] op_sel_hi:[1,0]
	v_cvt_pk_bf16_f32 v122, v122, v123
	v_pk_mul_f32 v[124:125], v[124:125], v[128:129]
	v_lshl_or_b32 v152, s18, 7, v175
	v_cvt_pk_bf16_f32 v123, v124, v125
	v_mul_f32_e32 v124, 0xbfb8aa3b, v118
	v_mul_f32_e32 v118, 0xbfb8aa3b, v119
	v_exp_f32_e32 v118, v118
	v_exp_f32_e32 v124, v124
	s_movk_i32 s6, 0xb00
	v_pk_mul_f32 v[110:111], v[110:111], v[48:49] op_sel_hi:[1,0]
	v_add_f32_e32 v118, 1.0, v118
	v_rcp_f32_e32 v125, v118
	v_pk_mul_f32 v[118:119], v[120:121], v[150:151] op_sel_hi:[1,0]
	v_add_f32_e32 v124, 1.0, v124
	v_mul_f32_e32 v120, 0xbfb8aa3b, v118
	v_pk_mul_f32 v[116:117], v[118:119], v[116:117]
	v_mul_f32_e32 v118, 0xbfb8aa3b, v119
	v_exp_f32_e32 v120, v120
	v_exp_f32_e32 v118, v118
	v_rcp_f32_e32 v124, v124
	v_pk_mul_f32 v[106:107], v[106:107], v[48:49] op_sel_hi:[1,0]
	v_add_f32_e32 v120, 1.0, v120
	v_add_f32_e32 v118, 1.0, v118
	v_rcp_f32_e32 v120, v120
	v_rcp_f32_e32 v121, v118
	v_pk_mul_f32 v[114:115], v[114:115], v[124:125]
	v_pk_mul_f32 v[106:107], v[110:111], v[106:107]
	v_cvt_pk_bf16_f32 v124, v114, v115
	v_mad_u64_u32 v[114:115], s[20:21], v177, s6, v[152:153]
	v_pk_mul_f32 v[116:117], v[116:117], v[120:121]
	v_mov_b32_e32 v115, v49
	v_cvt_pk_bf16_f32 v125, v116, v117
	v_lshl_add_u64 v[116:117], v[114:115], 1, s[12:13]
	v_mul_f32_e32 v115, 0xbfb8aa3b, v110
	v_mul_f32_e32 v110, 0xbfb8aa3b, v111
	v_exp_f32_e32 v110, v110
	global_store_dwordx4 v[116:117], v[122:125], off
	s_nop 1
	v_pk_mul_f32 v[108:109], v[108:109], v[48:49] op_sel_hi:[1,0]
	v_exp_f32_e32 v115, v115
	v_add_f32_e32 v110, 1.0, v110
	v_rcp_f32_e32 v117, v110
	v_pk_mul_f32 v[110:111], v[112:113], v[48:49] op_sel_hi:[1,0]
	v_add_f32_e32 v115, 1.0, v115
	v_mul_f32_e32 v112, 0xbfb8aa3b, v110
	v_pk_mul_f32 v[108:109], v[110:111], v[108:109]
	v_mul_f32_e32 v110, 0xbfb8aa3b, v111
	v_exp_f32_e32 v112, v112
	v_exp_f32_e32 v110, v110
	v_rcp_f32_e32 v116, v115
	v_pk_mul_f32 v[102:103], v[102:103], v[48:49] op_sel_hi:[1,0]
	v_add_f32_e32 v112, 1.0, v112
	v_add_f32_e32 v110, 1.0, v110
	v_rcp_f32_e32 v112, v112
	v_rcp_f32_e32 v113, v110
	v_pk_mul_f32 v[106:107], v[106:107], v[116:117]
	v_pk_mul_f32 v[98:99], v[98:99], v[48:49] op_sel_hi:[1,0]
	v_cvt_pk_bf16_f32 v106, v106, v107
	v_pk_mul_f32 v[108:109], v[108:109], v[112:113]
	v_pk_mul_f32 v[98:99], v[102:103], v[98:99]
	v_cvt_pk_bf16_f32 v107, v108, v109
	v_mul_f32_e32 v108, 0xbfb8aa3b, v102
	v_mul_f32_e32 v102, 0xbfb8aa3b, v103
	v_exp_f32_e32 v102, v102
	v_exp_f32_e32 v108, v108
	v_pk_mul_f32 v[100:101], v[100:101], v[48:49] op_sel_hi:[1,0]
	v_pk_mul_f32 v[94:95], v[94:95], v[148:149] op_sel_hi:[1,0]
	v_add_f32_e32 v102, 1.0, v102
	v_rcp_f32_e32 v109, v102
	v_pk_mul_f32 v[102:103], v[104:105], v[48:49] op_sel_hi:[1,0]
	v_add_f32_e32 v108, 1.0, v108
	v_mul_f32_e32 v48, 0xbfb8aa3b, v103
	v_exp_f32_e32 v48, v48
	v_rcp_f32_e32 v108, v108
	v_mul_f32_e32 v104, 0xbfb8aa3b, v102
	v_exp_f32_e32 v104, v104
	v_add_f32_e32 v48, 1.0, v48
	v_pk_mul_f32 v[98:99], v[98:99], v[108:109]
	v_rcp_f32_e32 v105, v48
	v_add_u32_e32 v48, 0xb000, v114
	v_add_f32_e32 v104, 1.0, v104
	v_cvt_pk_bf16_f32 v108, v98, v99
	v_lshl_add_u64 v[98:99], v[48:49], 1, s[12:13]
	v_mul_f32_e32 v48, 0xbfb8aa3b, v94
	v_rcp_f32_e32 v104, v104
	v_exp_f32_e32 v48, v48
	v_pk_mul_f32 v[100:101], v[102:103], v[100:101]
	v_pk_mul_f32 v[90:91], v[90:91], v[148:149] op_sel_hi:[1,0]
	v_pk_mul_f32 v[100:101], v[100:101], v[104:105]
	v_add_f32_e32 v48, 1.0, v48
	v_cvt_pk_bf16_f32 v109, v100, v101
	global_store_dwordx4 v[98:99], v[106:109], off
	s_nop 1
	v_rcp_f32_e32 v98, v48
	v_mul_f32_e32 v48, 0xbfb8aa3b, v95
	v_exp_f32_e32 v48, v48
	v_pk_mul_f32 v[90:91], v[94:95], v[90:91]
	v_pk_mul_f32 v[94:95], v[96:97], v[148:149] op_sel_hi:[1,0]
	v_pk_mul_f32 v[86:87], v[86:87], v[148:149] op_sel_hi:[1,0]
	v_add_f32_e32 v48, 1.0, v48
	v_rcp_f32_e32 v99, v48
	v_mul_f32_e32 v48, 0xbfb8aa3b, v94
	v_exp_f32_e32 v48, v48
	v_pk_mul_f32 v[92:93], v[92:93], v[148:149] op_sel_hi:[1,0]
	v_pk_mul_f32 v[90:91], v[90:91], v[98:99]
	v_pk_mul_f32 v[92:93], v[94:95], v[92:93]
	v_add_f32_e32 v48, 1.0, v48
	v_rcp_f32_e32 v96, v48
	v_mul_f32_e32 v48, 0xbfb8aa3b, v95
	v_exp_f32_e32 v48, v48
	v_cvt_pk_bf16_f32 v90, v90, v91
	v_pk_mul_f32 v[82:83], v[82:83], v[148:149] op_sel_hi:[1,0]
	v_pk_mul_f32 v[78:79], v[78:79], v[146:147] op_sel_hi:[1,0]
	v_add_f32_e32 v48, 1.0, v48
	v_rcp_f32_e32 v97, v48
	v_mul_f32_e32 v48, 0xbfb8aa3b, v86
	v_exp_f32_e32 v48, v48
	v_pk_mul_f32 v[82:83], v[86:87], v[82:83]
	v_pk_mul_f32 v[92:93], v[92:93], v[96:97]
	v_pk_mul_f32 v[84:85], v[84:85], v[148:149] op_sel_hi:[1,0]
	v_add_f32_e32 v48, 1.0, v48
	v_cvt_pk_bf16_f32 v91, v92, v93
	v_rcp_f32_e32 v92, v48
	v_mul_f32_e32 v48, 0xbfb8aa3b, v87
	v_exp_f32_e32 v48, v48
	v_pk_mul_f32 v[86:87], v[88:89], v[148:149] op_sel_hi:[1,0]
	v_pk_mul_f32 v[74:75], v[74:75], v[146:147] op_sel_hi:[1,0]
	v_pk_mul_f32 v[84:85], v[86:87], v[84:85]
	v_add_f32_e32 v48, 1.0, v48
	v_rcp_f32_e32 v93, v48
	v_mul_f32_e32 v48, 0xbfb8aa3b, v86
	v_exp_f32_e32 v48, v48
	v_pk_mul_f32 v[74:75], v[78:79], v[74:75]
	v_pk_mul_f32 v[82:83], v[82:83], v[92:93]
	v_pk_mul_f32 v[70:71], v[70:71], v[146:147] op_sel_hi:[1,0]
	v_add_f32_e32 v48, 1.0, v48
	v_rcp_f32_e32 v88, v48
	v_mul_f32_e32 v48, 0xbfb8aa3b, v87
	v_exp_f32_e32 v48, v48
	v_cvt_pk_bf16_f32 v92, v82, v83
	v_pk_mul_f32 v[76:77], v[76:77], v[146:147] op_sel_hi:[1,0]
	v_pk_mul_f32 v[66:67], v[66:67], v[146:147] op_sel_hi:[1,0]
	v_add_f32_e32 v48, 1.0, v48
	v_rcp_f32_e32 v89, v48
	v_add_u32_e32 v48, 0x16000, v114
	v_lshl_add_u64 v[82:83], v[48:49], 1, s[12:13]
	v_mul_f32_e32 v48, 0xbfb8aa3b, v78
	v_exp_f32_e32 v48, v48
	v_pk_mul_f32 v[84:85], v[84:85], v[88:89]
	v_pk_mul_f32 v[66:67], v[70:71], v[66:67]
	v_cvt_pk_bf16_f32 v93, v84, v85
	v_add_f32_e32 v48, 1.0, v48
	global_store_dwordx4 v[82:83], v[90:93], off
	s_nop 1
	v_rcp_f32_e32 v82, v48
	v_mul_f32_e32 v48, 0xbfb8aa3b, v79
	v_exp_f32_e32 v48, v48
	v_pk_mul_f32 v[78:79], v[80:81], v[146:147] op_sel_hi:[1,0]
	v_pk_mul_f32 v[62:63], v[62:63], v[144:145] op_sel_hi:[1,0]
	v_pk_mul_f32 v[76:77], v[78:79], v[76:77]
	v_add_f32_e32 v48, 1.0, v48
	v_rcp_f32_e32 v83, v48
	v_mul_f32_e32 v48, 0xbfb8aa3b, v78
	v_exp_f32_e32 v48, v48
	v_pk_mul_f32 v[68:69], v[68:69], v[146:147] op_sel_hi:[1,0]
	v_pk_mul_f32 v[74:75], v[74:75], v[82:83]
	v_pk_mul_f32 v[58:59], v[58:59], v[144:145] op_sel_hi:[1,0]
	v_add_f32_e32 v48, 1.0, v48
	v_rcp_f32_e32 v80, v48
	v_mul_f32_e32 v48, 0xbfb8aa3b, v79
	v_exp_f32_e32 v48, v48
	v_cvt_pk_bf16_f32 v74, v74, v75
	v_pk_mul_f32 v[58:59], v[62:63], v[58:59]
	v_pk_mul_f32 v[54:55], v[54:55], v[144:145] op_sel_hi:[1,0]
	v_add_f32_e32 v48, 1.0, v48
	v_rcp_f32_e32 v81, v48
	v_mul_f32_e32 v48, 0xbfb8aa3b, v70
	v_exp_f32_e32 v48, v48
	v_pk_mul_f32 v[60:61], v[60:61], v[144:145] op_sel_hi:[1,0]
	v_pk_mul_f32 v[76:77], v[76:77], v[80:81]
	v_pk_mul_f32 v[50:51], v[50:51], v[144:145] op_sel_hi:[1,0]
	v_add_f32_e32 v48, 1.0, v48
	v_cvt_pk_bf16_f32 v75, v76, v77
	v_rcp_f32_e32 v76, v48
	v_mul_f32_e32 v48, 0xbfb8aa3b, v71
	v_exp_f32_e32 v48, v48
	v_pk_mul_f32 v[70:71], v[72:73], v[146:147] op_sel_hi:[1,0]
	v_pk_mul_f32 v[50:51], v[54:55], v[50:51]
	v_pk_mul_f32 v[68:69], v[70:71], v[68:69]
	v_add_f32_e32 v48, 1.0, v48
	v_rcp_f32_e32 v77, v48
	v_mul_f32_e32 v48, 0xbfb8aa3b, v70
	v_exp_f32_e32 v48, v48
	v_pk_mul_f32 v[44:45], v[44:45], v[142:143] op_sel_hi:[1,0]
	v_pk_mul_f32 v[66:67], v[66:67], v[76:77]
	v_pk_mul_f32 v[40:41], v[40:41], v[142:143] op_sel_hi:[1,0]
	v_add_f32_e32 v48, 1.0, v48
	v_rcp_f32_e32 v72, v48
	v_mul_f32_e32 v48, 0xbfb8aa3b, v71
	v_exp_f32_e32 v48, v48
	v_cvt_pk_bf16_f32 v76, v66, v67
	v_pk_mul_f32 v[40:41], v[44:45], v[40:41]
	v_pk_mul_f32 v[52:53], v[52:53], v[144:145] op_sel_hi:[1,0]
	v_add_f32_e32 v48, 1.0, v48
	v_rcp_f32_e32 v73, v48
	v_add_u32_e32 v48, 0x21000, v114
	v_lshl_add_u64 v[66:67], v[48:49], 1, s[12:13]
	v_mul_f32_e32 v48, 0xbfb8aa3b, v62
	v_exp_f32_e32 v48, v48
	v_pk_mul_f32 v[68:69], v[68:69], v[72:73]
	v_pk_mul_f32 v[42:43], v[42:43], v[142:143] op_sel_hi:[1,0]
	v_cvt_pk_bf16_f32 v77, v68, v69
	v_add_f32_e32 v48, 1.0, v48
	global_store_dwordx4 v[66:67], v[74:77], off
	s_nop 1
	v_rcp_f32_e32 v66, v48
	v_mul_f32_e32 v48, 0xbfb8aa3b, v63
	v_exp_f32_e32 v48, v48
	v_pk_mul_f32 v[62:63], v[64:65], v[144:145] op_sel_hi:[1,0]
	v_pk_mul_f32 v[36:37], v[36:37], v[142:143] op_sel_hi:[1,0]
	v_pk_mul_f32 v[60:61], v[62:63], v[60:61]
	v_add_f32_e32 v48, 1.0, v48
	v_rcp_f32_e32 v67, v48
	v_mul_f32_e32 v48, 0xbfb8aa3b, v62
	v_exp_f32_e32 v48, v48
	v_pk_mul_f32 v[32:33], v[32:33], v[142:143] op_sel_hi:[1,0]
	v_pk_mul_f32 v[58:59], v[58:59], v[66:67]
	v_pk_mul_f32 v[32:33], v[36:37], v[32:33]
	v_add_f32_e32 v48, 1.0, v48
	v_rcp_f32_e32 v64, v48
	v_mul_f32_e32 v48, 0xbfb8aa3b, v63
	v_exp_f32_e32 v48, v48
	v_cvt_pk_bf16_f32 v58, v58, v59
	v_pk_mul_f32 v[34:35], v[34:35], v[142:143] op_sel_hi:[1,0]
	v_pk_mul_f32 v[28:29], v[28:29], v[140:141] op_sel_hi:[1,0]
	v_add_f32_e32 v48, 1.0, v48
	v_rcp_f32_e32 v65, v48
	v_mul_f32_e32 v48, 0xbfb8aa3b, v54
	v_exp_f32_e32 v48, v48
	v_pk_mul_f32 v[24:25], v[24:25], v[140:141] op_sel_hi:[1,0]
	v_pk_mul_f32 v[60:61], v[60:61], v[64:65]
	v_pk_mul_f32 v[24:25], v[28:29], v[24:25]
	v_add_f32_e32 v48, 1.0, v48
	v_cvt_pk_bf16_f32 v59, v60, v61
	v_rcp_f32_e32 v60, v48
	v_mul_f32_e32 v48, 0xbfb8aa3b, v55
	v_exp_f32_e32 v48, v48
	v_pk_mul_f32 v[54:55], v[56:57], v[144:145] op_sel_hi:[1,0]
	v_pk_mul_f32 v[26:27], v[26:27], v[140:141] op_sel_hi:[1,0]
	v_pk_mul_f32 v[52:53], v[54:55], v[52:53]
	v_add_f32_e32 v48, 1.0, v48
	v_rcp_f32_e32 v61, v48
	v_mul_f32_e32 v48, 0xbfb8aa3b, v54
	v_exp_f32_e32 v48, v48
	v_pk_mul_f32 v[20:21], v[20:21], v[140:141] op_sel_hi:[1,0]
	v_pk_mul_f32 v[50:51], v[50:51], v[60:61]
	v_pk_mul_f32 v[16:17], v[16:17], v[140:141] op_sel_hi:[1,0]
	v_add_f32_e32 v48, 1.0, v48
	v_rcp_f32_e32 v56, v48
	v_mul_f32_e32 v48, 0xbfb8aa3b, v55
	v_exp_f32_e32 v48, v48
	v_cvt_pk_bf16_f32 v60, v50, v51
	v_pk_mul_f32 v[16:17], v[20:21], v[16:17]
	v_pk_mul_f32 v[18:19], v[18:19], v[140:141] op_sel_hi:[1,0]
	v_add_f32_e32 v48, 1.0, v48
	v_rcp_f32_e32 v57, v48
	v_add_u32_e32 v48, 0x58000, v114
	v_lshl_add_u64 v[50:51], v[48:49], 1, s[12:13]
	v_mul_f32_e32 v48, 0xbfb8aa3b, v44
	v_mul_f32_e32 v44, 0xbfb8aa3b, v45
	v_exp_f32_e32 v44, v44
	v_pk_mul_f32 v[52:53], v[52:53], v[56:57]
	v_exp_f32_e32 v48, v48
	v_cvt_pk_bf16_f32 v61, v52, v53
	v_add_f32_e32 v44, 1.0, v44
	global_store_dwordx4 v[50:51], v[58:61], off
	s_nop 1
	v_rcp_f32_e32 v51, v44
	v_pk_mul_f32 v[44:45], v[46:47], v[142:143] op_sel_hi:[1,0]
	v_add_f32_e32 v48, 1.0, v48
	v_mul_f32_e32 v46, 0xbfb8aa3b, v44
	v_pk_mul_f32 v[42:43], v[44:45], v[42:43]
	v_mul_f32_e32 v44, 0xbfb8aa3b, v45
	v_exp_f32_e32 v46, v46
	v_exp_f32_e32 v44, v44
	v_rcp_f32_e32 v50, v48
	v_add_u32_e32 v48, 0x63000, v114
	v_add_f32_e32 v46, 1.0, v46
	v_add_f32_e32 v44, 1.0, v44
	v_rcp_f32_e32 v46, v46
	v_rcp_f32_e32 v47, v44
	v_pk_mul_f32 v[40:41], v[40:41], v[50:51]
	v_pk_mul_f32 v[12:13], v[12:13], v[138:139] op_sel_hi:[1,0]
	v_cvt_pk_bf16_f32 v40, v40, v41
	v_pk_mul_f32 v[42:43], v[42:43], v[46:47]
	v_pk_mul_f32 v[8:9], v[8:9], v[138:139] op_sel_hi:[1,0]
	v_cvt_pk_bf16_f32 v41, v42, v43
	v_mul_f32_e32 v42, 0xbfb8aa3b, v36
	v_mul_f32_e32 v36, 0xbfb8aa3b, v37
	v_exp_f32_e32 v36, v36
	v_exp_f32_e32 v42, v42
	v_pk_mul_f32 v[8:9], v[12:13], v[8:9]
	v_pk_mul_f32 v[10:11], v[10:11], v[138:139] op_sel_hi:[1,0]
	v_add_f32_e32 v36, 1.0, v36
	v_rcp_f32_e32 v43, v36
	v_pk_mul_f32 v[36:37], v[38:39], v[142:143] op_sel_hi:[1,0]
	v_add_f32_e32 v42, 1.0, v42
	v_mul_f32_e32 v38, 0xbfb8aa3b, v36
	v_pk_mul_f32 v[34:35], v[36:37], v[34:35]
	v_mul_f32_e32 v36, 0xbfb8aa3b, v37
	v_exp_f32_e32 v38, v38
	v_exp_f32_e32 v36, v36
	v_rcp_f32_e32 v42, v42
	v_pk_mul_f32 v[4:5], v[4:5], v[138:139] op_sel_hi:[1,0]
	v_add_f32_e32 v38, 1.0, v38
	v_add_f32_e32 v36, 1.0, v36
	v_rcp_f32_e32 v38, v38
	v_rcp_f32_e32 v39, v36
	v_pk_mul_f32 v[32:33], v[32:33], v[42:43]
	v_pk_mul_f32 v[0:1], v[0:1], v[138:139] op_sel_hi:[1,0]
	v_cvt_pk_bf16_f32 v42, v32, v33
	v_pk_mul_f32 v[34:35], v[34:35], v[38:39]
	v_lshl_add_u64 v[32:33], v[48:49], 1, s[12:13]
	v_cvt_pk_bf16_f32 v43, v34, v35
	global_store_dwordx4 v[32:33], v[40:43], off
	s_nop 1
	v_mul_f32_e32 v32, 0xbfb8aa3b, v28
	v_mul_f32_e32 v28, 0xbfb8aa3b, v29
	v_exp_f32_e32 v28, v28
	v_exp_f32_e32 v32, v32
	v_add_u32_e32 v48, 0x6e000, v114
	v_pk_mul_f32 v[0:1], v[4:5], v[0:1]
	v_add_f32_e32 v28, 1.0, v28
	v_rcp_f32_e32 v33, v28
	v_pk_mul_f32 v[28:29], v[30:31], v[140:141] op_sel_hi:[1,0]
	v_add_f32_e32 v32, 1.0, v32
	v_mul_f32_e32 v30, 0xbfb8aa3b, v28
	v_pk_mul_f32 v[26:27], v[28:29], v[26:27]
	v_mul_f32_e32 v28, 0xbfb8aa3b, v29
	v_exp_f32_e32 v30, v30
	v_exp_f32_e32 v28, v28
	v_rcp_f32_e32 v32, v32
	v_pk_mul_f32 v[2:3], v[2:3], v[138:139] op_sel_hi:[1,0]
	v_add_f32_e32 v30, 1.0, v30
	v_add_f32_e32 v28, 1.0, v28
	v_rcp_f32_e32 v30, v30
	v_rcp_f32_e32 v31, v28
	v_pk_mul_f32 v[24:25], v[24:25], v[32:33]
	s_mov_b64 s[38:39], -1
	v_cvt_pk_bf16_f32 v24, v24, v25
	v_pk_mul_f32 v[26:27], v[26:27], v[30:31]
	s_andn2_b64 vcc, exec, s[46:47]
	v_cvt_pk_bf16_f32 v25, v26, v27
	v_mul_f32_e32 v26, 0xbfb8aa3b, v20
	v_mul_f32_e32 v20, 0xbfb8aa3b, v21
	v_exp_f32_e32 v20, v20
	v_exp_f32_e32 v26, v26
	v_add_f32_e32 v20, 1.0, v20
	v_rcp_f32_e32 v27, v20
	v_pk_mul_f32 v[20:21], v[22:23], v[140:141] op_sel_hi:[1,0]
	v_add_f32_e32 v26, 1.0, v26
	v_mul_f32_e32 v22, 0xbfb8aa3b, v20
	v_pk_mul_f32 v[18:19], v[20:21], v[18:19]
	v_mul_f32_e32 v20, 0xbfb8aa3b, v21
	v_exp_f32_e32 v22, v22
	v_exp_f32_e32 v20, v20
	v_rcp_f32_e32 v26, v26
	v_add_f32_e32 v22, 1.0, v22
	v_add_f32_e32 v20, 1.0, v20
	v_rcp_f32_e32 v22, v22
	v_rcp_f32_e32 v23, v20
	v_pk_mul_f32 v[16:17], v[16:17], v[26:27]
	v_pk_mul_f32 v[18:19], v[18:19], v[22:23]
	v_cvt_pk_bf16_f32 v26, v16, v17
	v_lshl_add_u64 v[16:17], v[48:49], 1, s[12:13]
	v_cvt_pk_bf16_f32 v27, v18, v19
	global_store_dwordx4 v[16:17], v[24:27], off
	s_nop 1
	v_mul_f32_e32 v16, 0xbfb8aa3b, v12
	v_mul_f32_e32 v12, 0xbfb8aa3b, v13
	v_exp_f32_e32 v12, v12
	v_exp_f32_e32 v16, v16
	v_add_u32_e32 v48, 0x79000, v114
	v_add_f32_e32 v12, 1.0, v12
	v_rcp_f32_e32 v17, v12
	v_pk_mul_f32 v[12:13], v[14:15], v[138:139] op_sel_hi:[1,0]
	v_add_f32_e32 v16, 1.0, v16
	v_mul_f32_e32 v14, 0xbfb8aa3b, v12
	v_pk_mul_f32 v[10:11], v[12:13], v[10:11]
	v_mul_f32_e32 v12, 0xbfb8aa3b, v13
	v_exp_f32_e32 v14, v14
	v_exp_f32_e32 v12, v12
	v_rcp_f32_e32 v16, v16
	v_add_f32_e32 v14, 1.0, v14
	v_add_f32_e32 v12, 1.0, v12
	v_rcp_f32_e32 v14, v14
	v_rcp_f32_e32 v15, v12
	v_pk_mul_f32 v[8:9], v[8:9], v[16:17]
	v_pk_mul_f32 v[10:11], v[10:11], v[14:15]
	v_cvt_pk_bf16_f32 v8, v8, v9
	v_cvt_pk_bf16_f32 v9, v10, v11
	v_mul_f32_e32 v10, 0xbfb8aa3b, v4
	v_mul_f32_e32 v4, 0xbfb8aa3b, v5
	v_exp_f32_e32 v4, v4
	v_exp_f32_e32 v10, v10
	v_add_f32_e32 v4, 1.0, v4
	v_rcp_f32_e32 v11, v4
	v_pk_mul_f32 v[4:5], v[6:7], v[138:139] op_sel_hi:[1,0]
	v_add_f32_e32 v10, 1.0, v10
	v_mul_f32_e32 v6, 0xbfb8aa3b, v4
	v_pk_mul_f32 v[2:3], v[4:5], v[2:3]
	v_mul_f32_e32 v4, 0xbfb8aa3b, v5
	v_exp_f32_e32 v6, v6
	v_exp_f32_e32 v4, v4
	v_rcp_f32_e32 v10, v10
	v_add_f32_e32 v6, 1.0, v6
	v_add_f32_e32 v4, 1.0, v4
	v_rcp_f32_e32 v6, v6
	v_rcp_f32_e32 v7, v4
	v_pk_mul_f32 v[0:1], v[0:1], v[10:11]
	v_pk_mul_f32 v[2:3], v[2:3], v[6:7]
	v_cvt_pk_bf16_f32 v10, v0, v1
	v_cvt_pk_bf16_f32 v11, v2, v3
	v_lshl_add_u64 v[0:1], v[48:49], 1, s[12:13]
	global_store_dwordx4 v[0:1], v[8:11], off
	s_nop 1
	s_cbranch_vccnz .LBB0_1407
	s_andn2_b64 vcc, exec, s[2:3]
	s_cbranch_vccnz .LBB0_1406
	s_barrier
	s_branch .LBB0_1406
